# same as the 1.032x version plus 20 bytes of unreachable padding so the three GEMM mainloops after the scan code keep the baseline's instruction-fetch alignment
# baseline (speedup 1.0000x reference)
; DI float shfl_xor_(float v, int mask, int lane) { return __int_as_float(__builtin_amdgcn_ds_bpermute((lane ^ mask) << 2, __float_as_int(v))); }
; #define MFMA32(a, b, c) __builtin_amdgcn_mfma_f32_32x32x16_bf16((a), (b), (c), 0, 0, 0)
; DI void flash_update(FlashState& st, f32x16& sc0, f32x16& sc1, const bf16_t* VT, int vs, int qi, int hl) {
;     const bf16x8 va0 = ld_vfrag(VT, qi * vs + 4 * hl), vb0 = ld_vfrag(VT, (32 + qi) * vs + 4 * hl);
;     const bf16x8 va1 = ld_vfrag(VT, qi * vs + 32 + 4 * hl), vb1 = ld_vfrag(VT, (32 + qi) * vs + 32 + 4 * hl);
;     asm volatile("" ::: "memory");
;     float mt = -INFINITY;
; #pragma unroll
;     for (int i = 0; i < 16; ++i) mt = fmaxf(mt, fmaxf(sc0[i], sc1[i]));
;     mt = fmaxf(mt, shfl_xor_(mt, 32, qi + 32 * hl));
;     const float mnew = fmaxf(st.m, mt), muse = (mnew == -INFINITY) ? 0.f : mnew;
;     const float alpha = __builtin_amdgcn_exp2f(st.m - muse);
;     float ls = 0.f;
; #pragma unroll
;     for (int i = 0; i < 16; ++i) { sc0[i] = __builtin_amdgcn_exp2f(sc0[i] - muse); sc1[i] = __builtin_amdgcn_exp2f(sc1[i] - muse); ls += sc0[i] + sc1[i]; }
;     st.l = st.l * alpha + ls; st.m = mnew;
;     st.o0 *= alpha; st.o1 *= alpha;
;     {
;         const bf16x8 p0 = pack8(sc0[0], sc0[1], sc0[2], sc0[3], sc0[4], sc0[5], sc0[6], sc0[7]);
;         const bf16x8 p1 = pack8(sc1[0], sc1[1], sc1[2], sc1[3], sc1[4], sc1[5], sc1[6], sc1[7]);
;         const bf16x8 wa0 = ld_vfrag(VT, qi * vs + 16 + 4 * hl), wb0 = ld_vfrag(VT, (32 + qi) * vs + 16 + 4 * hl);
;         const bf16x8 wa1 = ld_vfrag(VT, qi * vs + 48 + 4 * hl), wb1 = ld_vfrag(VT, (32 + qi) * vs + 48 + 4 * hl);
;         st.o0 = MFMA32(va0, p0, st.o0); st.o1 = MFMA32(vb0, p0, st.o1); st.o0 = MFMA32(va1, p1, st.o0); st.o1 = MFMA32(vb1, p1, st.o1);
;         const bf16x8 r0 = pack8(sc0[8], sc0[9], sc0[10], sc0[11], sc0[12], sc0[13], sc0[14], sc0[15]);
;         const bf16x8 r1 = pack8(sc1[8], sc1[9], sc1[10], sc1[11], sc1[12], sc1[13], sc1[14], sc1[15]);
;         st.o0 = MFMA32(wa0, r0, st.o0); st.o1 = MFMA32(wb0, r0, st.o1); st.o0 = MFMA32(wa1, r1, st.o0); st.o1 = MFMA32(wb1, r1, st.o1);
.LBB0_805:
	s_or_b64 exec, exec, s[8:9]
	v_max_f32_e32 v0, v92, v92
	v_max_f32_e32 v38, v66, v66
	v_max_f32_e32 v0, v0, v38
	v_max_f32_e32 v38, v93, v93
	v_max_f32_e32 v39, v67, v67
	v_max_f32_e32 v38, v38, v39
	s_mov_b32 s0, 0xff800000
	v_max3_f32 v0, v0, s0, v38
	v_max_f32_e32 v38, v116, v116
	v_max_f32_e32 v39, v68, v68
	v_max_f32_e32 v38, v38, v39
	v_max_f32_e32 v39, v117, v117
	v_max_f32_e32 v40, v69, v69
	v_max_f32_e32 v39, v39, v40
	v_max3_f32 v0, v0, v38, v39
	v_max_f32_e32 v38, v118, v118
	v_max_f32_e32 v39, v70, v70
	v_max_f32_e32 v38, v38, v39
	v_max_f32_e32 v39, v119, v119
	v_max_f32_e32 v40, v71, v71
	v_max_f32_e32 v39, v39, v40
	v_max3_f32 v0, v0, v38, v39
	v_max_f32_e32 v38, v120, v120
	v_max_f32_e32 v39, v72, v72
	v_max_f32_e32 v38, v38, v39
	v_max_f32_e32 v39, v121, v121
	v_max_f32_e32 v40, v73, v73
	v_max_f32_e32 v39, v39, v40
	v_max3_f32 v0, v0, v38, v39
	v_max_f32_e32 v38, v130, v130
	v_max_f32_e32 v39, v74, v74
	v_max_f32_e32 v38, v38, v39
	v_max_f32_e32 v39, v131, v131
	v_max_f32_e32 v40, v75, v75
	v_max_f32_e32 v39, v39, v40
	v_max3_f32 v0, v0, v38, v39
	v_max_f32_e32 v38, v114, v114
	v_max_f32_e32 v39, v76, v76
	v_max_f32_e32 v38, v38, v39
	v_max_f32_e32 v39, v115, v115
	v_max_f32_e32 v40, v77, v77
	v_max_f32_e32 v39, v39, v40
	v_max3_f32 v0, v0, v38, v39
	v_max_f32_e32 v38, v96, v96
	v_max_f32_e32 v39, v78, v78
	v_max_f32_e32 v38, v38, v39
	v_max_f32_e32 v39, v97, v97
	v_max_f32_e32 v40, v79, v79
	v_max_f32_e32 v39, v39, v40
	v_max3_f32 v0, v0, v38, v39
	v_max_f32_e32 v38, v94, v94
	v_max_f32_e32 v39, v80, v80
	v_max_f32_e32 v38, v38, v39
	v_max_f32_e32 v39, v95, v95
	v_max_f32_e32 v40, v81, v81
	v_max_f32_e32 v39, v39, v40
	v_max3_f32 v0, v0, v38, v39
	ds_bpermute_b32 v38, v149, v0
	s_waitcnt lgkmcnt(2)
	v_add_u32_e32 v140, 0x2000, v155
	ds_read2_b64 v[34:37], v140 offset0:128 offset1:130
	v_add_u32_e32 v141, 0x3000, v158
	ds_read2_b64 v[62:65], v141 offset0:192 offset1:194
	ds_read2_b64 v[132:135], v140 offset0:136 offset1:138
	s_waitcnt lgkmcnt(4)
	ds_read2_b64 v[136:139], v141 offset0:200 offset1:202
	s_waitcnt lgkmcnt(4)
	v_max3_f32 v38, v160, v0, v38
	v_cmp_neq_f32_e64 s[0:1], s0, v38
	s_nop 1
	v_cndmask_b32_e64 v142, 0, v38, s[0:1]
	v_sub_f32_e32 v0, v92, v142
	v_exp_f32_e32 v39, v0
	v_sub_f32_e32 v0, v66, v142
	v_exp_f32_e32 v40, v0
	v_sub_f32_e32 v0, v93, v142
	v_exp_f32_e32 v41, v0
	v_sub_f32_e32 v0, v67, v142
	v_exp_f32_e32 v42, v0
	v_sub_f32_e32 v0, v116, v142
	v_exp_f32_e32 v43, v0
	v_sub_f32_e32 v0, v68, v142
	v_exp_f32_e32 v44, v0
	v_sub_f32_e32 v0, v117, v142
	v_exp_f32_e32 v45, v0
	v_sub_f32_e32 v0, v69, v142
	v_exp_f32_e32 v46, v0
	v_sub_f32_e32 v0, v118, v142
	v_exp_f32_e32 v47, v0
	v_sub_f32_e32 v0, v70, v142
	v_exp_f32_e32 v48, v0
	v_sub_f32_e32 v0, v119, v142
	v_exp_f32_e32 v49, v0
	v_sub_f32_e32 v0, v71, v142
	v_exp_f32_e32 v50, v0
	v_sub_f32_e32 v0, v120, v142
	v_exp_f32_e32 v51, v0
	v_sub_f32_e32 v0, v72, v142
	v_exp_f32_e32 v52, v0
	v_sub_f32_e32 v0, v121, v142
	v_exp_f32_e32 v53, v0
	v_sub_f32_e32 v0, v73, v142
	v_exp_f32_e32 v54, v0
	v_sub_f32_e32 v0, v130, v142
	v_exp_f32_e32 v55, v0
	v_sub_f32_e32 v0, v74, v142
	v_exp_f32_e32 v56, v0
	v_sub_f32_e32 v0, v131, v142
	v_exp_f32_e32 v57, v0
	v_sub_f32_e32 v0, v75, v142
	v_exp_f32_e32 v58, v0
	v_sub_f32_e32 v0, v160, v142
	v_exp_f32_e32 v0, v0
	v_cvt_pk_bf16_f32 v66, v39, v41
	v_cvt_pk_bf16_f32 v67, v43, v45
	v_cvt_pk_bf16_f32 v68, v47, v49
	v_pk_mul_f32 v[16:17], v[16:17], v[0:1] op_sel_hi:[1,0]
	v_pk_mul_f32 v[14:15], v[14:15], v[0:1] op_sel_hi:[1,0]
	v_pk_mul_f32 v[12:13], v[12:13], v[0:1] op_sel_hi:[1,0]
	v_pk_mul_f32 v[10:11], v[10:11], v[0:1] op_sel_hi:[1,0]
	v_pk_mul_f32 v[8:9], v[8:9], v[0:1] op_sel_hi:[1,0]
	v_pk_mul_f32 v[6:7], v[6:7], v[0:1] op_sel_hi:[1,0]
	v_pk_mul_f32 v[4:5], v[4:5], v[0:1] op_sel_hi:[1,0]
	v_pk_mul_f32 v[2:3], v[2:3], v[0:1] op_sel_hi:[1,0]
	v_pk_mul_f32 v[32:33], v[32:33], v[0:1] op_sel_hi:[1,0]
	v_cvt_pk_bf16_f32 v69, v51, v53
	v_pk_mul_f32 v[30:31], v[30:31], v[0:1] op_sel_hi:[1,0]
	v_pk_mul_f32 v[28:29], v[28:29], v[0:1] op_sel_hi:[1,0]
	v_pk_mul_f32 v[26:27], v[26:27], v[0:1] op_sel_hi:[1,0]
	v_pk_mul_f32 v[24:25], v[24:25], v[0:1] op_sel_hi:[1,0]
	v_pk_mul_f32 v[22:23], v[22:23], v[0:1] op_sel_hi:[1,0]
	v_pk_mul_f32 v[20:21], v[20:21], v[0:1] op_sel_hi:[1,0]
	v_pk_mul_f32 v[18:19], v[18:19], v[0:1] op_sel_hi:[1,0]
	s_waitcnt lgkmcnt(3)
	v_mfma_f32_32x32x16_bf16 v[2:17], v[34:37], v[66:69], v[2:17]
	ds_read2_b64 v[70:73], v141 offset0:196 offset1:198
	v_sub_f32_e32 v59, v114, v142
	v_sub_f32_e32 v34, v115, v142
	v_sub_f32_e32 v35, v96, v142
	v_sub_f32_e32 v36, v97, v142
	v_sub_f32_e32 v37, v94, v142
	v_sub_f32_e32 v61, v95, v142
	s_waitcnt lgkmcnt(3)
	v_mfma_f32_32x32x16_bf16 v[18:33], v[62:65], v[66:69], v[18:33]
	v_cvt_pk_bf16_f32 v62, v40, v42
	v_cvt_pk_bf16_f32 v63, v44, v46
	v_cvt_pk_bf16_f32 v64, v48, v50
	v_cvt_pk_bf16_f32 v65, v52, v54
	ds_read2_b64 v[66:69], v140 offset0:132 offset1:134
	v_exp_f32_e32 v59, v59
	v_exp_f32_e32 v34, v34
	s_waitcnt lgkmcnt(3)
	v_mfma_f32_32x32x16_bf16 v[2:17], v[132:135], v[62:65], v[2:17]
	v_exp_f32_e32 v35, v35
	v_exp_f32_e32 v36, v36
	v_exp_f32_e32 v37, v37
	v_exp_f32_e32 v61, v61
	v_sub_f32_e32 v60, v76, v142
	v_sub_f32_e32 v92, v77, v142
	v_cvt_pk_bf16_f32 v74, v55, v57
	s_waitcnt lgkmcnt(2)
	v_mfma_f32_32x32x16_bf16 v[18:33], v[136:139], v[62:65], v[18:33]
	v_cvt_pk_bf16_f32 v75, v59, v34
	v_cvt_pk_bf16_f32 v76, v35, v36
	v_cvt_pk_bf16_f32 v77, v37, v61
	v_exp_f32_e32 v62, v92
	ds_read2_b64 v[92:95], v140 offset0:140 offset1:142
	v_sub_f32_e32 v63, v78, v142
	v_sub_f32_e32 v64, v79, v142
	s_waitcnt lgkmcnt(1)
	v_mfma_f32_32x32x16_bf16 v[2:17], v[66:69], v[74:77], v[2:17]
	v_sub_f32_e32 v65, v80, v142
	v_sub_f32_e32 v66, v81, v142
	v_exp_f32_e32 v60, v60
	v_exp_f32_e32 v63, v63
	v_exp_f32_e32 v64, v64
	v_exp_f32_e32 v65, v65
	v_exp_f32_e32 v66, v66
	v_mfma_f32_32x32x16_bf16 v[18:33], v[70:73], v[74:77], v[18:33]
	ds_read2_b64 v[72:75], v141 offset0:204 offset1:206
	v_cvt_pk_bf16_f32 v68, v56, v58
	v_cvt_pk_bf16_f32 v69, v60, v62
	v_cvt_pk_bf16_f32 v70, v63, v64
	v_cvt_pk_bf16_f32 v71, v65, v66
	s_waitcnt lgkmcnt(0)
	s_barrier
; DI int tid_() { int t = threadIdx.x; asm volatile("" : "+v"(t)); return t; }
; #define MFMA32(a, b, c) __builtin_amdgcn_mfma_f32_32x32x16_bf16((a), (b), (c), 0, 0, 0)
; DI void flash_update(FlashState& st, f32x16& sc0, f32x16& sc1, const bf16_t* VT, int vs, int qi, int hl) {
;     ...
;         st.o0 = MFMA32(va0, p0, st.o0); st.o1 = MFMA32(vb0, p0, st.o1); st.o0 = MFMA32(va1, p1, st.o0); st.o1 = MFMA32(vb1, p1, st.o1);
;         const bf16x8 r0 = pack8(sc0[8], sc0[9], sc0[10], sc0[11], sc0[12], sc0[13], sc0[14], sc0[15]);
;         const bf16x8 r1 = pack8(sc1[8], sc1[9], sc1[10], sc1[11], sc1[12], sc1[13], sc1[14], sc1[15]);
;         st.o0 = MFMA32(wa0, r0, st.o0); st.o1 = MFMA32(wb0, r0, st.o1); st.o0 = MFMA32(wa1, r1, st.o0); st.o1 = MFMA32(wb1, r1, st.o1);
; DI void kv_store(const KVRegs& r, bf16_t* KT, bf16_t* VT) {
;     const int tid = tid_();
;     *(u32x4*)(KT + (tid >> 3) * KTS + (tid & 7) * 8) = r.k;
;     const int key = tid & 63, ch = tid >> 6;
; #pragma unroll
;     for (int j = 0; j < 8; ++j) VT[(ch * 8 + j) * KTS + key] = (bf16_t)((j & 1) ? (r.v[j >> 1] >> 16) : (r.v[j >> 1] & 0xFFFFu));
; }
	v_mfma_f32_32x32x16_bf16 v[2:17], v[92:95], v[68:71], v[2:17]
	v_mfma_f32_32x32x16_bf16 v[18:33], v[72:75], v[68:71], v[18:33]
	s_and_saveexec_b64 s[0:1], vcc
	s_cbranch_execz .LBB0_788
	v_mov_b32_e32 v67, v238
	s_nop 0
	v_ashrrev_i32_e32 v69, 3, v67
	v_lshlrev_b32_e32 v70, 4, v67
	v_mul_lo_u32 v68, v69, s74
	v_and_b32_e32 v70, 0x70, v70
	v_add3_u32 v68, 0, v68, v70
	v_and_b32_e32 v67, 63, v67
	s_waitcnt vmcnt(1)
	ds_write_b128 v68, v[82:85]
	v_and_b32_e32 v70, 0xffffff8, v69
	v_lshl_add_u32 v68, v67, 1, 0
	v_or_b32_e32 v67, 7, v69
	v_mad_u64_u32 v[70:71], s[6:7], v70, s74, v[68:69]
	v_mad_u64_u32 v[68:69], s[6:7], v67, s74, v[68:69]
	s_waitcnt vmcnt(0)
	ds_write_b16 v70, v86 offset:9216
	ds_write_b16_d16_hi v70, v86 offset:9360
	ds_write_b16 v70, v87 offset:9504
	ds_write_b16_d16_hi v70, v87 offset:9648
	ds_write_b16 v70, v88 offset:9792
	ds_write_b16_d16_hi v70, v88 offset:9936
	ds_write_b16 v70, v89 offset:10080
	ds_write_b16_d16_hi v68, v89 offset:9216
	s_branch .LBB0_788
	s_nop 0
	s_nop 0
	s_nop 0
	s_nop 0
	s_nop 0
